# 96 layer-1 ffn_in weight tiles (1200..1295) moved from the idle workgroups of ffn_in(0) to those of qkv(0)
# speedup vs baseline: 1.0087x; 1.0006x over previous
.LBB0_505:
	s_and_b64 s[0:1], s[0:1], exec
	s_movk_i32 s0, 0x4b0
	s_cselect_b32 s28, s0, 0xa10
	s_movk_i32 s0, 0x620
	s_cselect_b32 s30, s0, 0xb80
	s_add_i32 s33, s33, s28
	v_mov_b32_e32 v32, v156
	s_cmp_ge_i32 s33, s30
	s_cbranch_scc1 .LBB0_664
	s_cmpk_gt_i32 s33, 0x15f
	s_mov_b64 s[24:25], -1
	s_cbranch_scc0 .LBB0_577
	s_cmpk_gt_u32 s33, 0x20f
	s_cbranch_scc0 .LBB0_574
	s_cmpk_gt_u32 s33, 0x28f
	s_cbranch_scc0 .LBB0_571
	s_cmpk_gt_u32 s33, 0x2cf
	s_cbranch_scc0 .LBB0_568
	s_cmpk_gt_u32 s33, 0x30f
	s_cbranch_scc0 .LBB0_565
	s_cmpk_gt_u32 s33, 0x36f
	s_cbranch_scc0 .LBB0_562
	s_cmpk_gt_u32 s33, 0x3af
	s_cbranch_scc0 .LBB0_559
	s_cmpk_gt_u32 s33, 0x50f
	s_cbranch_scc0 .LBB0_556
	s_cmpk_gt_u32 s33, 0x5bf
	s_cbranch_scc0 .LBB0_553
	s_cmpk_gt_u32 s33, 0x61f
	s_cbranch_scc0 .LBB0_550
	s_cmpk_gt_u32 s33, 0x6cf
	s_cbranch_scc0 .LBB0_547
	s_cmpk_gt_u32 s33, 0x70f
	s_cbranch_scc0 .LBB0_544
	s_cmpk_gt_u32 s33, 0x78f
	s_cbranch_scc0 .LBB0_541
	s_cmpk_gt_u32 s33, 0x7cf
	s_cbranch_scc0 .LBB0_538
	s_cmpk_gt_u32 s33, 0x8cf
	s_cbranch_scc0 .LBB0_535
	s_cmpk_gt_u32 s33, 0x92f
	s_cbranch_scc0 .LBB0_532
	s_cmpk_gt_u32 s33, 0x96f
	s_cbranch_scc0 .LBB0_529
	s_cmpk_gt_u32 s33, 0xacf
	s_mov_b64 s[4:5], -1
	s_cbranch_scc0 .LBB0_525
	s_load_dwordx2 s[0:1], s[72:73], 0xd8
	s_add_i32 s31, s33, 0xfffff530
	s_mov_b64 s[4:5], 0
	s_waitcnt lgkmcnt(0)
	s_add_u32 s0, s0, 0x2100000
	s_addc_u32 s1, s1, 0

.LBB0_798:
	s_and_b32 s0, 0xffff, s5
	s_cmp_lg_u32 s0, 0
	s_cselect_b64 s[0:1], -1, 0
	s_cmp_lg_u64 s[0:1], 0
	s_addc_u32 s0, s4, 0
	s_cmpk_eq_i32 s0, 0x100
	s_cbranch_scc0 .LBB0_955
	v_readlane_b32 s0, v255, 6
	s_cmp_eq_u32 s0, 3
	v_readlane_b32 s4, v254, 0
	s_cselect_b64 s[0:1], -1, 0
	s_cmpk_lt_i32 s4, 0xc0
	s_cselect_b64 s[4:5], -1, 0
	s_or_b64 s[0:1], s[0:1], s[4:5]
	s_and_b64 vcc, exec, s[0:1]
	s_cbranch_vccnz .LBB0_955
	v_readlane_b32 s0, v255, 6
	s_cmp_eq_u32 s0, 1
	s_movk_i32 s0, 0x8d0
	s_cselect_b32 s4, s0, 0xa10
	s_movk_i32 s0, 0x610
	s_cselect_b32 s5, s0, 0x810
	v_readlane_b32 s0, v255, 18
	v_readlane_b32 s1, v255, 19
	s_and_b64 s[0:1], s[0:1], exec
	s_cselect_b32 s0, 0x250, s5
	v_readlane_b32 s1, v254, 0
	s_cselect_b32 s40, 0x4b0, s4
	s_add_i32 s41, s1, s0
	v_mov_b32_e32 v32, v156
	s_cmp_ge_i32 s41, s40
	s_cbranch_scc1 .LBB0_955
	s_cmpk_gt_i32 s41, 0x15f
	s_mov_b64 s[24:25], -1
	s_cbranch_scc0 .LBB0_868
	s_cmpk_gt_u32 s41, 0x20f
	s_cbranch_scc0 .LBB0_865
	s_cmpk_gt_u32 s41, 0x28f
	s_cbranch_scc0 .LBB0_862
	s_cmpk_gt_u32 s41, 0x2cf
	s_cbranch_scc0 .LBB0_859
	s_cmpk_gt_u32 s41, 0x30f
	s_cbranch_scc0 .LBB0_856
	s_cmpk_gt_u32 s41, 0x36f
	s_cbranch_scc0 .LBB0_853
	s_cmpk_gt_u32 s41, 0x3af
	s_cbranch_scc0 .LBB0_850
	s_cmpk_gt_u32 s41, 0x50f
	s_cbranch_scc0 .LBB0_847
	s_cmpk_gt_u32 s41, 0x5bf
	s_cbranch_scc0 .LBB0_844
	s_cmpk_gt_u32 s41, 0x61f
	s_cbranch_scc0 .LBB0_841
	s_cmpk_gt_u32 s41, 0x6cf
	s_cbranch_scc0 .LBB0_838
	s_cmpk_gt_u32 s41, 0x70f
	s_cbranch_scc0 .LBB0_835
	s_cmpk_gt_u32 s41, 0x78f
	s_cbranch_scc0 .LBB0_832
	s_cmpk_gt_u32 s41, 0x7cf
	s_cbranch_scc0 .LBB0_829
	s_cmpk_gt_u32 s41, 0x8cf
	s_cbranch_scc0 .LBB0_826
	s_cmpk_gt_u32 s41, 0x92f
	s_cbranch_scc0 .LBB0_823
	s_cmpk_gt_u32 s41, 0x96f
	s_mov_b64 s[4:5], -1
	s_cbranch_scc0 .LBB0_819
	s_load_dwordx2 s[0:1], s[72:73], 0xd0
	s_add_i32 s33, s41, 0xfffff690
	s_mov_b64 s[4:5], 0
	s_waitcnt lgkmcnt(0)
	s_add_u32 s0, s0, 0x4200000
	s_addc_u32 s1, s1, 0
